# skinny GEMM tiles (meta rows / gate-rank columns): all 32 operand loads of a tile issued up front with counted vmcnt, on top of v31
# speedup vs baseline: 1.0247x; 1.0247x over previous
; __device__ __forceinline__ unsigned pk2(float lo, float hi) { unsigned r; asm("v_cvt_pk_bf16_f32 %0, %1, %2" : "=v"(r) : "v"(lo), "v"(hi)); return r; }
; __device__ __forceinline__ int crow16(int r, int hi) { return (r & 3) + 8 * (r >> 2) + 4 * hi; }
; template <int PH>
; __device__ __forceinline__ void run_phase(Ctx& c, LAS unsigned char* lds, char* lds_generic) {
;     ...
;             for (int t = blockIdx.x; t < n_meta + n_lr; t += c.G) {
;                 const int row0 = t < n_meta ? NREAL + 32 * (t & 1) : 32 * (t - n_meta), col0 = t < n_meta ? 32 * (t >> 1) : ATT_N;
;                 const bf16_t* ap = Ap + (size_t)(row0 + r32) * DM + c.wave * 256 + hi * 64; const bf16_t* bp = Bp + (size_t)(col0 + r32) * DM + c.wave * 256 + hi * 64;
;                 f32x16 acc = {};
; #pragma unroll
;                 for (int s = 0; s < 2; ++s) {
;                     bf16x8 av[8], bv[8];
; #pragma unroll
;                     for (int j = 0; j < 8; ++j) { av[j] = *(const bf16x8*)(ap + s * 128 + 8 * j); bv[j] = *(const bf16x8*)(bp + s * 128 + 8 * j); }
; #pragma unroll
;                     for (int j = 0; j < 8; ++j) acc = __builtin_amdgcn_mfma_f32_32x32x16_bf16(av[j], bv[j], acc, 0, 0, 0);
;                 }
; #pragma unroll
;                 for (int r = 0; r < 16; ++r) RED[c.wave * 1024 + crow16(r, hi) * 32 + r32] = acc[r];
;                 __syncthreads();
;                 { const int e = c.tid * 2; float v0 = 0.f, v1 = 0.f;
; #pragma unroll
;                   for (int w = 0; w < 8; ++w) { v0 += RED[w * 1024 + e]; v1 += RED[w * 1024 + e + 1]; }
;                   *(unsigned*)(Op + (size_t)(row0 + (e >> 5)) * LDC + col0 + (e & 31)) = pk2(v0, v1); }
;                 __syncthreads();
.LBB0_122:
	s_and_b32 s3, s6, 32
	s_and_b32 s2, s0, 0xffffffe0
	s_or_b32 s10, s3, 0x4000
	v_or_b32_e32 v0, s2, v26
	v_or_b32_e32 v2, s10, v26
	v_ashrrev_i32_e32 v1, 31, v0
	v_lshlrev_b32_e32 v16, 12, v2
	v_lshlrev_b64 v[0:1], 12, v[0:1]
	v_lshl_add_u64 v[54:55], v[18:19], 0, v[16:17]
	v_lshl_add_u64 v[56:57], v[20:21], 0, v[0:1]
	global_load_dwordx4 v[120:123], v[54:55], off
	global_load_dwordx4 v[124:127], v[56:57], off
	global_load_dwordx4 v[128:131], v[54:55], off offset:16
	global_load_dwordx4 v[132:135], v[56:57], off offset:16
	global_load_dwordx4 v[136:139], v[54:55], off offset:32
	global_load_dwordx4 v[140:143], v[56:57], off offset:32
	global_load_dwordx4 v[144:147], v[54:55], off offset:48
	global_load_dwordx4 v[148:151], v[56:57], off offset:48
	global_load_dwordx4 v[152:155], v[54:55], off offset:64
	global_load_dwordx4 v[156:159], v[56:57], off offset:64
	global_load_dwordx4 v[160:163], v[54:55], off offset:80
	global_load_dwordx4 v[164:167], v[56:57], off offset:80
	global_load_dwordx4 v[168:171], v[54:55], off offset:96
	global_load_dwordx4 v[172:175], v[56:57], off offset:96
	global_load_dwordx4 v[176:179], v[54:55], off offset:112
	global_load_dwordx4 v[180:183], v[56:57], off offset:112
	global_load_dwordx4 v[184:187], v[54:55], off offset:256
	global_load_dwordx4 v[188:191], v[56:57], off offset:256
	global_load_dwordx4 v[192:195], v[54:55], off offset:272
	global_load_dwordx4 v[196:199], v[56:57], off offset:272
	global_load_dwordx4 v[204:207], v[54:55], off offset:288
	global_load_dwordx4 v[208:211], v[56:57], off offset:288
	global_load_dwordx4 v[212:215], v[54:55], off offset:304
	global_load_dwordx4 v[216:219], v[56:57], off offset:304
	global_load_dwordx4 v[220:223], v[54:55], off offset:320
	global_load_dwordx4 v[224:227], v[56:57], off offset:320
	global_load_dwordx4 v[228:231], v[54:55], off offset:336
	global_load_dwordx4 v[232:235], v[56:57], off offset:336
	global_load_dwordx4 v[236:239], v[54:55], off offset:352
	global_load_dwordx4 v[240:243], v[56:57], off offset:352
	global_load_dwordx4 v[244:247], v[54:55], off offset:368
	global_load_dwordx4 v[248:251], v[56:57], off offset:368
	v_add_u32_e32 v16, s10, v28
	s_ashr_i32 s3, s2, 31
	s_add_i32 s9, s9, s63
	s_add_i32 s0, s0, s1
	s_add_i32 s6, s6, s7
	s_cmpk_gt_i32 s9, 0x17f
	v_mad_i64_i32 v[38:39], s[10:11], v16, s8, v[22:23]
	v_lshl_add_u64 v[38:39], s[2:3], 1, v[38:39]
	v_lshl_add_u64 v[38:39], v[38:39], 0, v[24:25]
	s_waitcnt vmcnt(30)
	v_mfma_f32_32x32x16_bf16 v[0:15], v[120:123], v[124:127], 0
	s_waitcnt vmcnt(28)
	v_mfma_f32_32x32x16_bf16 v[0:15], v[128:131], v[132:135], v[0:15]
	s_waitcnt vmcnt(26)
	v_mfma_f32_32x32x16_bf16 v[0:15], v[136:139], v[140:143], v[0:15]
	s_waitcnt vmcnt(24)
	v_mfma_f32_32x32x16_bf16 v[0:15], v[144:147], v[148:151], v[0:15]
	s_waitcnt vmcnt(22)
	v_mfma_f32_32x32x16_bf16 v[0:15], v[152:155], v[156:159], v[0:15]
	s_waitcnt vmcnt(20)
	v_mfma_f32_32x32x16_bf16 v[0:15], v[160:163], v[164:167], v[0:15]
	s_waitcnt vmcnt(18)
	v_mfma_f32_32x32x16_bf16 v[0:15], v[168:171], v[172:175], v[0:15]
	s_waitcnt vmcnt(16)
	v_mfma_f32_32x32x16_bf16 v[0:15], v[176:179], v[180:183], v[0:15]
	s_waitcnt vmcnt(14)
	v_mfma_f32_32x32x16_bf16 v[0:15], v[184:187], v[188:191], v[0:15]
	s_waitcnt vmcnt(12)
	v_mfma_f32_32x32x16_bf16 v[0:15], v[192:195], v[196:199], v[0:15]
	s_waitcnt vmcnt(10)
	v_mfma_f32_32x32x16_bf16 v[0:15], v[204:207], v[208:211], v[0:15]
	s_waitcnt vmcnt(8)
	v_mfma_f32_32x32x16_bf16 v[0:15], v[212:215], v[216:219], v[0:15]
	s_waitcnt vmcnt(6)
	v_mfma_f32_32x32x16_bf16 v[0:15], v[220:223], v[224:227], v[0:15]
	s_waitcnt vmcnt(4)
	v_mfma_f32_32x32x16_bf16 v[0:15], v[228:231], v[232:235], v[0:15]
	s_waitcnt vmcnt(2)
	v_mfma_f32_32x32x16_bf16 v[0:15], v[236:239], v[240:243], v[0:15]
	s_waitcnt vmcnt(0)
	v_mfma_f32_32x32x16_bf16 v[0:15], v[244:247], v[248:251], v[0:15]
	s_nop 11
	ds_write2_b32 v29, v0, v1 offset1:32
	ds_write2_b32 v29, v2, v3 offset0:64 offset1:96
	ds_write2_b32 v30, v4, v5 offset1:32
	ds_write2_b32 v30, v6, v7 offset0:64 offset1:96
	ds_write2_b32 v31, v8, v9 offset1:32
	ds_write2_b32 v31, v10, v11 offset0:64 offset1:96
	ds_write2_b32 v32, v12, v13 offset1:32
	ds_write2_b32 v32, v14, v15 offset0:64 offset1:96
	s_waitcnt lgkmcnt(0)
	s_barrier
	ds_read2st64_b64 v[0:3], v27 offset1:8
	ds_read2st64_b64 v[4:7], v27 offset0:16 offset1:24
	ds_read2st64_b64 v[8:11], v27 offset0:32 offset1:40
	ds_read2st64_b64 v[12:15], v27 offset0:48 offset1:56
	s_waitcnt lgkmcnt(3)
	v_add_f32_e32 v0, 0, v0
	v_add_f32_e32 v1, 0, v1
	v_add_f32_e32 v0, v0, v2
	v_add_f32_e32 v1, v1, v3
	s_waitcnt lgkmcnt(2)
	v_add_f32_e32 v0, v0, v4
	v_add_f32_e32 v1, v1, v5
	v_add_f32_e32 v0, v0, v6
	v_add_f32_e32 v1, v1, v7
	s_waitcnt lgkmcnt(1)
	v_add_f32_e32 v0, v0, v8
	v_add_f32_e32 v1, v1, v9
	v_add_f32_e32 v0, v0, v10
	v_add_f32_e32 v1, v1, v11
	s_waitcnt lgkmcnt(0)
	v_add_f32_e32 v0, v0, v12
	v_add_f32_e32 v1, v1, v13
	v_add_f32_e32 v0, v0, v14
	v_add_f32_e32 v1, v1, v15
	v_cvt_pk_bf16_f32 v0, v0, v1
	global_store_dword v[38:39], v0, off
	s_barrier
	s_cbranch_scc0 .LBB0_122

; __device__ __forceinline__ unsigned pk2(float lo, float hi) { unsigned r; asm("v_cvt_pk_bf16_f32 %0, %1, %2" : "=v"(r) : "v"(lo), "v"(hi)); return r; }
; __device__ __forceinline__ int crow16(int r, int hi) { return (r & 3) + 8 * (r >> 2) + 4 * hi; }
; template <int PH>
; __device__ __forceinline__ void run_phase(Ctx& c, LAS unsigned char* lds, char* lds_generic) {
;     ...
;             for (int t = blockIdx.x; t < n_meta + n_lr; t += c.G) {
;                 const int row0 = t < n_meta ? NREAL + 32 * (t & 1) : 32 * (t - n_meta), col0 = t < n_meta ? 32 * (t >> 1) : ATT_N;
;                 const bf16_t* ap = Ap + (size_t)(row0 + r32) * DM + c.wave * 256 + hi * 64; const bf16_t* bp = Bp + (size_t)(col0 + r32) * DM + c.wave * 256 + hi * 64;
;                 f32x16 acc = {};
; #pragma unroll
;                 for (int s = 0; s < 2; ++s) {
;                     bf16x8 av[8], bv[8];
; #pragma unroll
;                     for (int j = 0; j < 8; ++j) { av[j] = *(const bf16x8*)(ap + s * 128 + 8 * j); bv[j] = *(const bf16x8*)(bp + s * 128 + 8 * j); }
; #pragma unroll
;                     for (int j = 0; j < 8; ++j) acc = __builtin_amdgcn_mfma_f32_32x32x16_bf16(av[j], bv[j], acc, 0, 0, 0);
;                 }
; #pragma unroll
;                 for (int r = 0; r < 16; ++r) RED[c.wave * 1024 + crow16(r, hi) * 32 + r32] = acc[r];
;                 __syncthreads();
;                 { const int e = c.tid * 2; float v0 = 0.f, v1 = 0.f;
; #pragma unroll
;                   for (int w = 0; w < 8; ++w) { v0 += RED[w * 1024 + e]; v1 += RED[w * 1024 + e + 1]; }
;                   *(unsigned*)(Op + (size_t)(row0 + (e >> 5)) * LDC + col0 + (e & 31)) = pk2(v0, v1); }
;                 __syncthreads();
.LBB0_380:
	s_and_b32 s3, s6, 32
	s_and_b32 s2, s0, 0xffffffe0
	s_or_b32 s9, s3, 0x4000
	v_or_b32_e32 v0, s2, v24
	v_or_b32_e32 v2, s9, v24
	v_ashrrev_i32_e32 v1, 31, v0
	v_lshlrev_b32_e32 v16, 12, v2
	v_lshlrev_b64 v[0:1], 12, v[0:1]
	v_lshl_add_u64 v[52:53], v[18:19], 0, v[16:17]
	v_lshl_add_u64 v[54:55], v[20:21], 0, v[0:1]
	global_load_dwordx4 v[120:123], v[52:53], off
	global_load_dwordx4 v[124:127], v[54:55], off
	global_load_dwordx4 v[128:131], v[52:53], off offset:16
	global_load_dwordx4 v[132:135], v[54:55], off offset:16
	global_load_dwordx4 v[136:139], v[52:53], off offset:32
	global_load_dwordx4 v[140:143], v[54:55], off offset:32
	global_load_dwordx4 v[144:147], v[52:53], off offset:48
	global_load_dwordx4 v[148:151], v[54:55], off offset:48
	global_load_dwordx4 v[152:155], v[52:53], off offset:64
	global_load_dwordx4 v[156:159], v[54:55], off offset:64
	global_load_dwordx4 v[160:163], v[52:53], off offset:80
	global_load_dwordx4 v[164:167], v[54:55], off offset:80
	global_load_dwordx4 v[168:171], v[52:53], off offset:96
	global_load_dwordx4 v[172:175], v[54:55], off offset:96
	global_load_dwordx4 v[176:179], v[52:53], off offset:112
	global_load_dwordx4 v[180:183], v[54:55], off offset:112
	global_load_dwordx4 v[184:187], v[52:53], off offset:256
	global_load_dwordx4 v[188:191], v[54:55], off offset:256
	global_load_dwordx4 v[192:195], v[52:53], off offset:272
	global_load_dwordx4 v[196:199], v[54:55], off offset:272
	global_load_dwordx4 v[204:207], v[52:53], off offset:288
	global_load_dwordx4 v[208:211], v[54:55], off offset:288
	global_load_dwordx4 v[212:215], v[52:53], off offset:304
	global_load_dwordx4 v[216:219], v[54:55], off offset:304
	global_load_dwordx4 v[220:223], v[52:53], off offset:320
	global_load_dwordx4 v[224:227], v[54:55], off offset:320
	global_load_dwordx4 v[228:231], v[52:53], off offset:336
	global_load_dwordx4 v[232:235], v[54:55], off offset:336
	global_load_dwordx4 v[236:239], v[52:53], off offset:352
	global_load_dwordx4 v[240:243], v[54:55], off offset:352
	global_load_dwordx4 v[244:247], v[52:53], off offset:368
	global_load_dwordx4 v[248:251], v[54:55], off offset:368
	s_ashr_i32 s3, s2, 31
	s_add_i32 s8, s8, s63
	s_add_i32 s0, s0, s1
	s_add_i32 s6, s6, s7
	s_cmpk_gt_i32 s8, 0x7f
	v_add_u32_e32 v36, s9, v26
	v_ashrrev_i32_e32 v37, 31, v36
	v_lshlrev_b64 v[36:37], 12, v[36:37]
	v_lshl_add_u64 v[36:37], s[4:5], 0, v[36:37]
	v_lshl_add_u64 v[36:37], s[2:3], 1, v[36:37]
	v_lshl_add_u64 v[36:37], v[36:37], 0, v[22:23]
	s_waitcnt vmcnt(30)
	v_mfma_f32_32x32x16_bf16 v[0:15], v[120:123], v[124:127], 0
	s_waitcnt vmcnt(28)
	v_mfma_f32_32x32x16_bf16 v[0:15], v[128:131], v[132:135], v[0:15]
	s_waitcnt vmcnt(26)
	v_mfma_f32_32x32x16_bf16 v[0:15], v[136:139], v[140:143], v[0:15]
	s_waitcnt vmcnt(24)
	v_mfma_f32_32x32x16_bf16 v[0:15], v[144:147], v[148:151], v[0:15]
	s_waitcnt vmcnt(22)
	v_mfma_f32_32x32x16_bf16 v[0:15], v[152:155], v[156:159], v[0:15]
	s_waitcnt vmcnt(20)
	v_mfma_f32_32x32x16_bf16 v[0:15], v[160:163], v[164:167], v[0:15]
	s_waitcnt vmcnt(18)
	v_mfma_f32_32x32x16_bf16 v[0:15], v[168:171], v[172:175], v[0:15]
	s_waitcnt vmcnt(16)
	v_mfma_f32_32x32x16_bf16 v[0:15], v[176:179], v[180:183], v[0:15]
	s_waitcnt vmcnt(14)
	v_mfma_f32_32x32x16_bf16 v[0:15], v[184:187], v[188:191], v[0:15]
	s_waitcnt vmcnt(12)
	v_mfma_f32_32x32x16_bf16 v[0:15], v[192:195], v[196:199], v[0:15]
	s_waitcnt vmcnt(10)
	v_mfma_f32_32x32x16_bf16 v[0:15], v[204:207], v[208:211], v[0:15]
	s_waitcnt vmcnt(8)
	v_mfma_f32_32x32x16_bf16 v[0:15], v[212:215], v[216:219], v[0:15]
	s_waitcnt vmcnt(6)
	v_mfma_f32_32x32x16_bf16 v[0:15], v[220:223], v[224:227], v[0:15]
	s_waitcnt vmcnt(4)
	v_mfma_f32_32x32x16_bf16 v[0:15], v[228:231], v[232:235], v[0:15]
	s_waitcnt vmcnt(2)
	v_mfma_f32_32x32x16_bf16 v[0:15], v[236:239], v[240:243], v[0:15]
	s_waitcnt vmcnt(0)
	v_mfma_f32_32x32x16_bf16 v[0:15], v[244:247], v[248:251], v[0:15]
	s_nop 11
	ds_write2_b32 v27, v0, v1 offset1:32
	ds_write2_b32 v27, v2, v3 offset0:64 offset1:96
	ds_write2_b32 v28, v4, v5 offset1:32
	ds_write2_b32 v28, v6, v7 offset0:64 offset1:96
	ds_write2_b32 v29, v8, v9 offset1:32
	ds_write2_b32 v29, v10, v11 offset0:64 offset1:96
	ds_write2_b32 v30, v12, v13 offset1:32
	ds_write2_b32 v30, v14, v15 offset0:64 offset1:96
	s_waitcnt lgkmcnt(0)
	s_barrier
	ds_read2st64_b64 v[0:3], v25 offset1:8
	ds_read2st64_b64 v[4:7], v25 offset0:16 offset1:24
	ds_read2st64_b64 v[8:11], v25 offset0:32 offset1:40
	ds_read2st64_b64 v[12:15], v25 offset0:48 offset1:56
	s_waitcnt lgkmcnt(3)
	v_add_f32_e32 v0, 0, v0
	v_add_f32_e32 v1, 0, v1
	v_add_f32_e32 v0, v0, v2
	v_add_f32_e32 v1, v1, v3
	s_waitcnt lgkmcnt(2)
	v_add_f32_e32 v0, v0, v4
	v_add_f32_e32 v1, v1, v5
	v_add_f32_e32 v0, v0, v6
	v_add_f32_e32 v1, v1, v7
	s_waitcnt lgkmcnt(1)
	v_add_f32_e32 v0, v0, v8
	v_add_f32_e32 v1, v1, v9
	v_add_f32_e32 v0, v0, v10
	v_add_f32_e32 v1, v1, v11
	s_waitcnt lgkmcnt(0)
	v_add_f32_e32 v0, v0, v12
	v_add_f32_e32 v1, v1, v13
	v_add_f32_e32 v0, v0, v14
	v_add_f32_e32 v1, v1, v15
	v_cvt_pk_bf16_f32 v0, v0, v1
	global_store_dword v[36:37], v0, off
	s_barrier
	s_cbranch_scc0 .LBB0_380

; __device__ __forceinline__ void xcd_barrier(const XcdBarrier& b) {
;     ...
;     __syncthreads();
.LBB0_458:
	s_or_b64 exec, exec, s[2:3]
	s_waitcnt lgkmcnt(0)
	s_barrier
	s_nop 0
	s_nop 0
	s_nop 0
	s_nop 0
	s_nop 0
	s_nop 0
	s_nop 0
	s_nop 0
	s_nop 0
	s_nop 0
	s_nop 0
	s_nop 0
	s_nop 0
	s_nop 0

; __device__ __forceinline__ unsigned pk2(float lo, float hi) { unsigned r; asm("v_cvt_pk_bf16_f32 %0, %1, %2" : "=v"(r) : "v"(lo), "v"(hi)); return r; }
; __device__ __forceinline__ int crow16(int r, int hi) { return (r & 3) + 8 * (r >> 2) + 4 * hi; }
; template <int PH>
; __device__ __forceinline__ void run_phase(Ctx& c, LAS unsigned char* lds, char* lds_generic) {
;     ...
;             for (int t = blockIdx.x; t < n_meta + n_lr; t += c.G) {
;                 const int row0 = t < n_meta ? NREAL + 32 * (t & 1) : 32 * (t - n_meta), col0 = t < n_meta ? 32 * (t >> 1) : ATT_N;
;                 const bf16_t* ap = Ap + (size_t)(row0 + r32) * DM + c.wave * 256 + hi * 64; const bf16_t* bp = Bp + (size_t)(col0 + r32) * DM + c.wave * 256 + hi * 64;
;                 f32x16 acc = {};
; #pragma unroll
;                 for (int s = 0; s < 2; ++s) {
;                     bf16x8 av[8], bv[8];
; #pragma unroll
;                     for (int j = 0; j < 8; ++j) { av[j] = *(const bf16x8*)(ap + s * 128 + 8 * j); bv[j] = *(const bf16x8*)(bp + s * 128 + 8 * j); }
; #pragma unroll
;                     for (int j = 0; j < 8; ++j) acc = __builtin_amdgcn_mfma_f32_32x32x16_bf16(av[j], bv[j], acc, 0, 0, 0);
;                 }
; #pragma unroll
;                 for (int r = 0; r < 16; ++r) RED[c.wave * 1024 + crow16(r, hi) * 32 + r32] = acc[r];
;                 __syncthreads();
;                 { const int e = c.tid * 2; float v0 = 0.f, v1 = 0.f;
; #pragma unroll
;                   for (int w = 0; w < 8; ++w) { v0 += RED[w * 1024 + e]; v1 += RED[w * 1024 + e + 1]; }
;                   *(unsigned*)(Op + (size_t)(row0 + (e >> 5)) * LDC + col0 + (e & 31)) = pk2(v0, v1); }
;                 __syncthreads();
.LBB0_562:
	s_and_b32 s2, s6, 32
	s_add_i32 s3, s6, 0xffffcfc0
	s_and_b32 s10, s0, 0xffffffe0
	s_bitset1_b32 s2, 14
	s_cmpk_lt_i32 s9, 0x182
	s_cselect_b32 s3, s2, s3
	s_cselect_b32 s2, s10, 0x1800
	v_or_b32_e32 v16, s3, v26
	v_or_b32_e32 v0, s2, v26
	v_lshlrev_b64 v[2:3], 12, v[16:17]
	v_ashrrev_i32_e32 v1, 31, v0
	v_lshl_add_u64 v[8:9], v[18:19], 0, v[2:3]
	v_lshlrev_b64 v[0:1], 12, v[0:1]
	v_lshl_add_u64 v[102:103], v[20:21], 0, v[0:1]
	global_load_dwordx4 v[120:123], v[8:9], off
	global_load_dwordx4 v[124:127], v[102:103], off
	global_load_dwordx4 v[128:131], v[8:9], off offset:16
	global_load_dwordx4 v[132:135], v[102:103], off offset:16
	global_load_dwordx4 v[136:139], v[8:9], off offset:32
	global_load_dwordx4 v[140:143], v[102:103], off offset:32
	global_load_dwordx4 v[144:147], v[8:9], off offset:48
	global_load_dwordx4 v[148:151], v[102:103], off offset:48
	global_load_dwordx4 v[152:155], v[8:9], off offset:64
	global_load_dwordx4 v[156:159], v[102:103], off offset:64
	global_load_dwordx4 v[160:163], v[8:9], off offset:80
	global_load_dwordx4 v[164:167], v[102:103], off offset:80
	global_load_dwordx4 v[168:171], v[8:9], off offset:96
	global_load_dwordx4 v[172:175], v[102:103], off offset:96
	global_load_dwordx4 v[176:179], v[8:9], off offset:112
	global_load_dwordx4 v[180:183], v[102:103], off offset:112
	global_load_dwordx4 v[184:187], v[8:9], off offset:256
	global_load_dwordx4 v[188:191], v[102:103], off offset:256
	global_load_dwordx4 v[192:195], v[8:9], off offset:272
	global_load_dwordx4 v[196:199], v[102:103], off offset:272
	global_load_dwordx4 v[204:207], v[8:9], off offset:288
	global_load_dwordx4 v[208:211], v[102:103], off offset:288
	global_load_dwordx4 v[212:215], v[8:9], off offset:304
	global_load_dwordx4 v[216:219], v[102:103], off offset:304
	global_load_dwordx4 v[220:223], v[8:9], off offset:320
	global_load_dwordx4 v[224:227], v[102:103], off offset:320
	global_load_dwordx4 v[228:231], v[8:9], off offset:336
	global_load_dwordx4 v[232:235], v[102:103], off offset:336
	global_load_dwordx4 v[236:239], v[8:9], off offset:352
	global_load_dwordx4 v[240:243], v[102:103], off offset:352
	global_load_dwordx4 v[244:247], v[8:9], off offset:368
	global_load_dwordx4 v[248:251], v[102:103], off offset:368
	v_add_u32_e32 v16, s3, v28
	s_ashr_i32 s3, s2, 31
	s_add_i32 s9, s9, s63
	s_add_i32 s0, s0, s1
	s_add_i32 s6, s6, s7
	s_cmpk_gt_i32 s9, 0x381
	v_mad_i64_i32 v[38:39], s[10:11], v16, s8, v[22:23]
	v_lshl_add_u64 v[38:39], s[2:3], 1, v[38:39]
	v_lshl_add_u64 v[38:39], v[38:39], 0, v[24:25]
	s_waitcnt vmcnt(30)
	v_mfma_f32_32x32x16_bf16 v[0:15], v[120:123], v[124:127], 0
	s_waitcnt vmcnt(28)
	v_mfma_f32_32x32x16_bf16 v[0:15], v[128:131], v[132:135], v[0:15]
	s_waitcnt vmcnt(26)
	v_mfma_f32_32x32x16_bf16 v[0:15], v[136:139], v[140:143], v[0:15]
	s_waitcnt vmcnt(24)
	v_mfma_f32_32x32x16_bf16 v[0:15], v[144:147], v[148:151], v[0:15]
	s_waitcnt vmcnt(22)
	v_mfma_f32_32x32x16_bf16 v[0:15], v[152:155], v[156:159], v[0:15]
	s_waitcnt vmcnt(20)
	v_mfma_f32_32x32x16_bf16 v[0:15], v[160:163], v[164:167], v[0:15]
	s_waitcnt vmcnt(18)
	v_mfma_f32_32x32x16_bf16 v[0:15], v[168:171], v[172:175], v[0:15]
	s_waitcnt vmcnt(16)
	v_mfma_f32_32x32x16_bf16 v[0:15], v[176:179], v[180:183], v[0:15]
	s_waitcnt vmcnt(14)
	v_mfma_f32_32x32x16_bf16 v[0:15], v[184:187], v[188:191], v[0:15]
	s_waitcnt vmcnt(12)
	v_mfma_f32_32x32x16_bf16 v[0:15], v[192:195], v[196:199], v[0:15]
	s_waitcnt vmcnt(10)
	v_mfma_f32_32x32x16_bf16 v[0:15], v[204:207], v[208:211], v[0:15]
	s_waitcnt vmcnt(8)
	v_mfma_f32_32x32x16_bf16 v[0:15], v[212:215], v[216:219], v[0:15]
	s_waitcnt vmcnt(6)
	v_mfma_f32_32x32x16_bf16 v[0:15], v[220:223], v[224:227], v[0:15]
	s_waitcnt vmcnt(4)
	v_mfma_f32_32x32x16_bf16 v[0:15], v[228:231], v[232:235], v[0:15]
	s_waitcnt vmcnt(2)
	v_mfma_f32_32x32x16_bf16 v[0:15], v[236:239], v[240:243], v[0:15]
	s_waitcnt vmcnt(0)
	v_mfma_f32_32x32x16_bf16 v[0:15], v[244:247], v[248:251], v[0:15]
	s_nop 11
	ds_write2_b32 v29, v0, v1 offset1:32
	ds_write2_b32 v29, v2, v3 offset0:64 offset1:96
	ds_write2_b32 v30, v4, v5 offset1:32
	ds_write2_b32 v30, v6, v7 offset0:64 offset1:96
	ds_write2_b32 v31, v8, v9 offset1:32
	ds_write2_b32 v31, v10, v11 offset0:64 offset1:96
	ds_write2_b32 v32, v12, v13 offset1:32
	ds_write2_b32 v32, v14, v15 offset0:64 offset1:96
	s_waitcnt lgkmcnt(0)
	s_barrier
	ds_read2st64_b64 v[0:3], v27 offset1:8
	ds_read2st64_b64 v[4:7], v27 offset0:16 offset1:24
	ds_read2st64_b64 v[8:11], v27 offset0:32 offset1:40
	ds_read2st64_b64 v[12:15], v27 offset0:48 offset1:56
	s_waitcnt lgkmcnt(3)
	v_add_f32_e32 v0, 0, v0
	v_add_f32_e32 v1, 0, v1
	v_add_f32_e32 v0, v0, v2
	v_add_f32_e32 v1, v1, v3
	s_waitcnt lgkmcnt(2)
	v_add_f32_e32 v0, v0, v4
	v_add_f32_e32 v1, v1, v5
	v_add_f32_e32 v0, v0, v6
	v_add_f32_e32 v1, v1, v7
	s_waitcnt lgkmcnt(1)
	v_add_f32_e32 v0, v0, v8
	v_add_f32_e32 v1, v1, v9
	v_add_f32_e32 v0, v0, v10
	v_add_f32_e32 v1, v1, v11
	s_waitcnt lgkmcnt(0)
	v_add_f32_e32 v0, v0, v12
	v_add_f32_e32 v1, v1, v13
	v_add_f32_e32 v0, v0, v14
	v_add_f32_e32 v1, v1, v15
	v_cvt_pk_bf16_f32 v0, v0, v1
	global_store_dword v[38:39], v0, off
	s_barrier
	s_cbranch_scc0 .LBB0_562
